# up-phase tile order reversed (pn descending) so ACT columns written last are read first by down
# speedup vs baseline: 1.0007x; 1.0007x over previous
.LBB0_147:
	s_cmp_ge_i32 s66, s90
	s_cselect_b64 s[2:3], -1, 0
	s_cmp_lt_i32 s66, s91
	s_cselect_b64 s[4:5], -1, 0
	s_and_b64 s[6:7], s[2:3], s[4:5]
	s_andn2_b64 vcc, exec, s[6:7]
	s_cbranch_vccnz .LBB0_166
	s_mov_b64 s[4:5], s[86:87]
	s_mov_b32 s2, s67
	v_mov_b32_e32 v1, v0
	s_waitcnt vmcnt(0)
	v_mov_b32_e32 v18, v0
	s_cmpk_gt_i32 s2, 0xaff
	v_readfirstlane_b32 s11, v18
	s_cbranch_scc1 .LBB0_166
	v_lshlrev_b32_e32 v1, 4, v18
	v_add_u32_e32 v2, 0x2000, v1
	s_waitcnt lgkmcnt(0)
	v_ashrrev_i32_e32 v3, 31, v2
	v_lshrrev_b32_e32 v3, 22, v3
	v_add_u32_e32 v3, v2, v3
	v_ashrrev_i32_e32 v19, 10, v3
	v_mul_i32_i24_e32 v3, 0x400, v19
	v_sub_u32_e32 v2, v2, v3
	v_lshrrev_b32_e32 v3, 4, v2
	v_bitop3_b32 v2, v3, v2, 32 bitop3:0x6c
	v_readlane_b32 s0, v254, 17
	v_ashrrev_i32_e32 v3, 31, v2
	s_mul_i32 s80, s0, 0x1600000
	s_add_u32 s3, s4, 0x2fe00000
	v_lshrrev_b32_e32 v3, 26, v3
	s_addc_u32 s28, s5, 0
	s_lshl_b64 s[8:9], s[80:81], 1
	v_add_u32_e32 v3, v2, v3
	v_lshlrev_b32_e32 v4, 3, v19
	v_readlane_b32 s1, v254, 18
	s_add_u32 s0, s4, s8
	v_ashrrev_i32_e32 v20, 6, v3
	v_and_b32_e32 v4, -16, v4
	s_addc_u32 s1, s5, s9
	v_add_u32_e32 v4, v20, v4
	s_add_u32 s29, s0, 0x200000
	v_and_b32_e32 v5, 3, v20
	s_mov_b32 s0, 0xfffe0
	s_waitcnt vmcnt(4)
	v_lshrrev_b32_e32 v6, 2, v4
	v_lshlrev_b32_e32 v7, 1, v4
	v_and_b32_e32 v3, 0xc0, v3
	v_and_or_b32 v5, v4, s0, v5
	v_and_b32_e32 v6, 4, v6
	v_and_b32_e32 v7, 24, v7
	v_sub_u32_e32 v2, v2, v3
	v_or3_b32 v5, v5, v6, v7
	v_lshlrev_b32_e32 v6, 5, v19
	v_ashrrev_i16_sdwa v2, v237, sext(v2) dst_sel:DWORD dst_unused:UNUSED_PAD src0_sel:DWORD src1_sel:BYTE_0
	v_and_b32_e32 v6, 32, v6
	v_bfe_i32 v21, v2, 0, 16
	v_add_lshl_u32 v2, v6, v21, 1
	v_lshl_add_u32 v130, v5, 12, v2
	v_lshl_add_u32 v132, v4, 12, v2
	v_bfe_i32 v2, v18, 27, 1
	v_lshrrev_b32_e32 v2, 22, v2
	v_add_u32_e32 v2, v1, v2
	v_and_b32_e32 v2, 0xfffffc00, v2
	v_sub_u32_e32 v1, v1, v2
	v_lshrrev_b32_e32 v2, 4, v1
	v_ashrrev_i32_e32 v3, 31, v18
	v_bitop3_b32 v1, v2, v1, 32 bitop3:0x6c
	v_lshrrev_b32_e32 v3, 26, v3
	v_ashrrev_i32_e32 v2, 31, v1
	v_add_u32_e32 v3, v18, v3
	v_lshrrev_b32_e32 v2, 26, v2
	v_ashrrev_i32_e32 v23, 6, v3
	v_add_u32_e32 v2, v1, v2
	v_lshlrev_b32_e32 v3, 3, v23
	v_ashrrev_i32_e32 v22, 6, v2
	v_and_b32_e32 v3, -16, v3
	s_addc_u32 s30, s1, 0
	v_add_u32_e32 v3, v22, v3
	v_and_b32_e32 v4, 3, v22
	s_ashr_i32 s34, s2, 31
	v_and_or_b32 v4, v3, s0, v4
	s_lshr_b32 s0, s34, 29
	s_add_i32 s0, s2, s0
	s_ashr_i32 s14, s11, 6
	s_ashr_i32 s1, s0, 3
	s_and_b32 s0, s0, -8
	s_ashr_i32 s15, s11, 8
	s_lshl_b32 s31, s14, 10
	s_sub_i32 s0, s2, s0
	s_cmp_lt_i32 s0, 0
	s_movk_i32 s8, 0x161
	s_cselect_b32 s8, s8, 0x160
	s_mul_i32 s0, s0, s8
	s_add_i32 s0, s0, s1
	s_mul_hi_i32 s1, s0, 0x2e8ba2e9
	s_lshr_b32 s8, s1, 31
	s_ashr_i32 s1, s1, 6
	s_add_i32 s1, s1, s8
	s_lshl_b32 s8, s1, 3
	s_mulk_i32 s1, 0x160
	s_sub_i32 s0, s0, s1
	v_lshrrev_b32_e32 v5, 2, v3
	v_lshlrev_b32_e32 v6, 1, v3
	v_and_b32_e32 v2, 0xc0, v2
	s_bfe_u32 s1, s0, 0x3001c
	v_and_b32_e32 v5, 4, v5
	v_and_b32_e32 v6, 24, v6
	v_sub_u32_e32 v1, v1, v2
	s_add_i32 s1, s0, s1
	v_or3_b32 v4, v4, v5, v6
	v_lshlrev_b32_e32 v5, 5, v23
	v_ashrrev_i16_sdwa v1, v237, sext(v1) dst_sel:DWORD dst_unused:UNUSED_PAD src0_sel:DWORD src1_sel:BYTE_0
	s_sext_i32_i16 s9, s1
	s_and_b32 s1, s1, 0xfff8
	v_and_b32_e32 v5, 32, v5
	v_bfe_i32 v24, v1, 0, 16
	s_sub_i32 s0, s0, s1
	v_add_lshl_u32 v1, v5, v24, 1
	s_sext_i32_i16 s0, s0
	v_lshl_add_u32 v186, v4, 12, v1
	v_lshl_add_u32 v134, v3, 12, v1
	s_add_i32 s20, s8, s0
	v_ashrrev_i32_e32 v1, 1, v18
	s_lshr_b32 s10, s9, 3
	s_sub_i32 s10, 43, s10
	v_lshl_add_u32 v2, s20, 8, v1
	s_ashr_i32 s21, s20, 31
	s_bfe_i64 s[12:13], s[10:11], 0x100000
	v_ashrrev_i32_e32 v3, 31, v2
	s_lshl_b64 s[8:9], s[20:21], 20
	s_lshl_b64 s[12:13], s[12:13], 20
	v_lshlrev_b64 v[2:3], 7, v[2:3]
	v_and_b32_e32 v25, 1, v18
	s_add_u32 s24, s29, s12
	v_lshl_add_u64 v[2:3], s[4:5], 0, v[2:3]
	v_lshlrev_b32_e32 v4, 6, v25
	v_mov_b32_e32 v5, v187
	s_addc_u32 s25, s30, s13
	v_lshl_add_u64 v[2:3], v[2:3], 0, v[4:5]
	s_mov_b64 s[12:13], 0x33e00000
	s_mov_b32 s0, 0x33e00000
	v_lshl_add_u64 v[14:15], v[2:3], 0, s[12:13]
	v_add_co_u32_e32 v2, vcc, s0, v2
	s_add_i32 s35, s31, 0
	s_nop 0
	v_addc_co_u32_e32 v3, vcc, 0, v3, vcc
	s_add_i32 m0, s35, 0x10000
	global_load_dwordx4 v[10:13], v[2:3], off
	s_nop 0
	global_load_dwordx4 v[2:5], v[14:15], off offset:48
	global_load_dwordx4 v[6:9], v[14:15], off offset:32
	s_nop 0
	global_load_dwordx4 v[14:17], v[14:15], off offset:16
	s_nop 0
	global_load_lds_dwordx4 v186, s[24:25]
	s_add_i32 m0, s35, 0x12000
	s_add_u32 s12, s24, 0x80000
	global_load_lds_dwordx4 v130, s[24:25]
	s_addc_u32 s13, s25, 0
	s_add_i32 m0, s35, 0x14000
	s_nop 0
	global_load_lds_dwordx4 v186, s[12:13]
	s_add_i32 m0, s35, 0x16000
	s_add_u32 s22, s3, s8
	s_addc_u32 s23, s28, s9
	s_add_i32 s36, s35, 0x2000
	global_load_lds_dwordx4 v130, s[12:13]
	s_mov_b32 m0, s35
	s_add_u32 s8, s22, 0x80000
	global_load_lds_dwordx4 v134, s[22:23]
	s_mov_b32 m0, s36
	s_addc_u32 s9, s23, 0
	s_add_i32 s37, s35, 0x4000
	global_load_lds_dwordx4 v132, s[22:23]
	s_mov_b32 m0, s37
	s_add_i32 s38, s35, 0x6000
	global_load_lds_dwordx4 v134, s[8:9]
	s_mov_b32 m0, s38
	s_cmp_eq_u32 s15, 1
	global_load_lds_dwordx4 v132, s[8:9]
	s_cselect_b64 s[8:9], -1, 0
	s_cmp_lg_u32 s15, 1
	s_cbranch_scc1 .LBB0_151
	s_barrier

.LBB0_156:
	s_add_i32 s44, s44, 1
	s_mul_i32 s0, s44, s69
	s_mul_hi_u32 s1, s44, s71
	s_add_i32 s1, s1, s0
	s_mul_i32 s0, s44, s71
	s_add_u32 s16, s0, s2
	s_addc_u32 s17, s1, s34
	v_mov_b64_e32 v[2:3], 0xb00
	v_cmp_lt_i64_e64 s[4:5], s[16:17], v[2:3]
	v_mov_b64_e32 v[2:3], 0xaff
	v_cmp_gt_i64_e32 vcc, s[16:17], v[2:3]
	s_cbranch_vccnz .LBB0_158
	s_ashr_i32 s0, s16, 31
	s_lshr_b32 s0, s0, 29
	s_add_i32 s0, s16, s0
	s_ashr_i32 s1, s0, 3
	s_and_b32 s0, s0, -8
	s_sub_i32 s0, s16, s0
	s_cmp_lt_i32 s0, 0
	s_movk_i32 s12, 0x161
	s_cselect_b32 s12, s12, 0x160
	s_mul_i32 s0, s0, s12
	s_add_i32 s0, s0, s1
	s_mul_hi_i32 s1, s0, 0x2e8ba2e9
	s_lshr_b32 s12, s1, 31
	s_ashr_i32 s1, s1, 6
	s_add_i32 s1, s1, s12
	s_lshl_b32 s13, s1, 3
	s_sub_i32 s12, 64, s13
	s_min_i32 s14, s12, 8
	s_abs_i32 s12, s14
	v_cvt_f32_u32_e32 v2, s12
	s_sub_i32 s16, 0, s12
	s_mulk_i32 s1, 0x160
	s_sub_i32 s0, s0, s1
	v_rcp_iflag_f32_e32 v2, v2
	s_abs_i32 s1, s0
	s_xor_b32 s15, s0, s14
	s_ashr_i32 s15, s15, 31
	v_mul_f32_e32 v2, 0x4f7ffffe, v2
	v_cvt_u32_f32_e32 v2, v2
	s_nop 0
	v_readfirstlane_b32 s17, v2
	s_mul_i32 s16, s16, s17
	s_mul_hi_u32 s16, s17, s16
	s_add_i32 s17, s17, s16
	s_mul_hi_u32 s16, s1, s17
	s_mul_i32 s17, s16, s12
	s_sub_i32 s1, s1, s17
	s_add_i32 s18, s16, 1
	s_sub_i32 s17, s1, s12
	s_cmp_ge_u32 s1, s12
	s_cselect_b32 s16, s18, s16
	s_cselect_b32 s1, s17, s1
	s_add_i32 s17, s16, 1
	s_cmp_ge_u32 s1, s12
	s_cselect_b32 s1, s17, s16
	s_xor_b32 s1, s1, s15
	s_sub_i32 s12, s1, s15
	s_mul_i32 s1, s12, s14
	s_sub_i32 s0, s0, s1
	s_add_i32 s14, s13, s0
	s_sub_i32 s12, 43, s12
